# GEMM k-loops (UP, INPROJ): MFMA fragment registers double-buffered, next group's ds_reads issued between MFMAs with counted lgkmcnt
# speedup vs baseline: 1.0222x; 1.0179x over previous
; #define MFMA(a, b, c) __builtin_amdgcn_mfma_f32_32x32x16_bf16((a), (b), (c), 0, 0, 0)
;     ...
;     auto issue_at = [&](int mm0, int nn0, int kt, int buf) {
;       char* lb = L0 + buf * BUFB;
; #pragma unroll
;       for (int i = 0; i < 4; ++i) {
;         const int seg = wv * 4 + i, row = seg * 8 + gl_row;
;         const int c = (lane & 7) ^ ((row >> 1) & 7);
;         const u16* ap = (kt < g.split) ? g.a0 + (size_t)(mm0 + row) * g.ld0 + kt * g.ks0 : g.a1 + (size_t)(mm0 + row) * g.ld1 + (kt - g.split) * 64;
;         __builtin_amdgcn_global_load_lds((const unsigned*)(ap + c * 8), (__attribute__((address_space(3))) unsigned*)(lb + seg * 1024 + lane * 16), 16, 0, 0);
;       }
; #pragma unroll
;       for (int i = 0; i < BN / 64; ++i) {
;         const int seg = wv * (BN / 64) + i, row = seg * 8 + gl_row;
;         const int c = (lane & 7) ^ ((row >> 1) & 7);
;         __builtin_amdgcn_global_load_lds((const unsigned*)(g.W + (size_t)(nn0 + row) * g.K + kt * 64 + c * 8),
;                                          (__attribute__((address_space(3))) unsigned*)(lb + 256 * 128 + seg * 1024 + lane * 16), 16, 0, 0);
;       }
;     };
;     ...
;     auto compute2 = [&](int buf) {
;       const char* lb = L0 + buf * BUFB;
; #pragma unroll
;       for (int ks = 0; ks < 4; ++ks) {
;         const int c = ks * 2 + hh;
;         bf16x8 wf[2], xf[MI];
; #pragma unroll
;         for (int j = 0; j < 2; ++j) { const int r = wn * 64 + j * 32 + l32; wf[j] = *(const bf16x8*)(lb + 256 * 128 + r * 128 + ((c ^ ((r >> 1) & 7)) << 4)); }
; #pragma unroll
;         for (int i = 0; i < MI; ++i) { const int r = wm * (MI * 32) + i * 32 + l32; xf[i] = *(const bf16x8*)(lb + r * 128 + ((c ^ ((r >> 1) & 7)) << 4)); }
; #pragma unroll
;         for (int i = 0; i < MI; ++i) {
;           acc[i][0] = MFMA(wf[0], xf[i], acc[i][0]);
;           acc[i][1] = MFMA(wf[1], xf[i], acc[i][1]);
;         }
;       }
;     };
.LBB0_798:
	s_and_b32 s14, s11, 0x10000
	s_xor_b32 s15, s14, 0x10000
	s_add_i32 s15, s15, 0
	s_add_i32 s14, s14, 0
	v_add_u32_e32 v0, s14, v175
	v_add_u32_e32 v176, v0, v171
	v_add_u32_e32 v0, v0, v170
	ds_read_b128 v[200:203], v176 offset:32768
	ds_read_b128 v[204:207], v176 offset:36864
	ds_read_b128 v[208:211], v0
	ds_read_b128 v[212:215], v0 offset:4096
	ds_read_b128 v[216:219], v0 offset:8192
	ds_read_b128 v[220:223], v0 offset:12288
	v_add3_u32 v0, s15, v168, v169
	v_add3_u32 v178, s15, v160, v169
	v_readfirstlane_b32 s16, v0
	v_lshl_add_u64 v[176:177], v[152:153], 0, s[2:3]
	s_mov_b32 m0, s16
	v_readfirstlane_b32 s16, v178
	v_add3_u32 v199, s15, v162, v169
	global_load_lds_dwordx4 v[176:177], off
	v_lshl_add_u64 v[176:177], v[150:151], 0, s[2:3]
	s_mov_b32 m0, s16
	v_readfirstlane_b32 s16, v199
	v_add3_u32 v254, s15, v166, v169
	global_load_lds_dwordx4 v[176:177], off
	v_lshl_add_u64 v[176:177], v[148:149], 0, s[2:3]
	s_mov_b32 m0, s16
	v_readfirstlane_b32 s15, v254
	v_add_u32_e32 v0, 0x8000, v0
	global_load_lds_dwordx4 v[176:177], off
	v_lshl_add_u64 v[176:177], v[146:147], 0, s[2:3]
	s_mov_b32 m0, s15
	v_readfirstlane_b32 s15, v0
	v_add_u32_e32 v0, 0x8000, v178
	global_load_lds_dwordx4 v[176:177], off
	v_lshl_add_u64 v[176:177], v[144:145], 0, s[2:3]
	s_mov_b32 m0, s15
	v_readfirstlane_b32 s15, v0
	v_add_u32_e32 v0, 0x8000, v199
	global_load_lds_dwordx4 v[176:177], off
	v_lshl_add_u64 v[176:177], v[142:143], 0, s[2:3]
	s_mov_b32 m0, s15
	v_readfirstlane_b32 s15, v0
	v_add_u32_e32 v0, 0x8000, v254
	global_load_lds_dwordx4 v[176:177], off
	v_lshl_add_u64 v[176:177], v[140:141], 0, s[2:3]
	s_mov_b32 m0, s15
	v_readfirstlane_b32 s15, v0
	global_load_lds_dwordx4 v[176:177], off
	v_lshl_add_u64 v[176:177], v[138:139], 0, s[2:3]
	s_mov_b32 m0, s15
	global_load_lds_dwordx4 v[176:177], off
	v_add_u32_e32 v0, s14, v174
	v_add_u32_e32 v176, v0, v171
	v_add_u32_e32 v0, v0, v170
	s_waitcnt lgkmcnt(3)
	v_mfma_f32_32x32x16_bf16 v[114:129], v[200:203], v[208:211], v[114:129]
	s_add_i32 s11, s11, 0x10000
	s_add_u32 s2, s2, 0x80
	s_addc_u32 s3, s3, 0
	s_cmpk_eq_i32 s2, 0x780
	ds_read_b128 v[224:227], v176 offset:32768
	v_mfma_f32_32x32x16_bf16 v[98:113], v[204:207], v[208:211], v[98:113]
	ds_read_b128 v[228:231], v176 offset:36864
	s_waitcnt lgkmcnt(4)
	v_mfma_f32_32x32x16_bf16 v[82:97], v[200:203], v[212:215], v[82:97]
	ds_read_b128 v[232:235], v0
	v_mfma_f32_32x32x16_bf16 v[66:81], v[204:207], v[212:215], v[66:81]
	ds_read_b128 v[240:243], v0 offset:4096
	s_waitcnt lgkmcnt(5)
	v_mfma_f32_32x32x16_bf16 v[50:65], v[200:203], v[216:219], v[50:65]
	ds_read_b128 v[244:247], v0 offset:8192
	v_mfma_f32_32x32x16_bf16 v[34:49], v[204:207], v[216:219], v[34:49]
	ds_read_b128 v[248:251], v0 offset:12288
	s_waitcnt lgkmcnt(6)
	v_mfma_f32_32x32x16_bf16 v[18:33], v[200:203], v[220:223], v[18:33]
	v_mfma_f32_32x32x16_bf16 v[2:17], v[204:207], v[220:223], v[2:17]
	v_add_u32_e32 v0, s14, v173
	v_add_u32_e32 v176, v0, v171
	v_add_u32_e32 v0, v0, v170
	s_waitcnt lgkmcnt(3)
	v_mfma_f32_32x32x16_bf16 v[114:129], v[224:227], v[232:235], v[114:129]
	ds_read_b128 v[200:203], v176 offset:32768
	v_mfma_f32_32x32x16_bf16 v[98:113], v[228:231], v[232:235], v[98:113]
	ds_read_b128 v[204:207], v176 offset:36864
	s_waitcnt lgkmcnt(4)
	v_mfma_f32_32x32x16_bf16 v[82:97], v[224:227], v[240:243], v[82:97]
	ds_read_b128 v[208:211], v0
	v_mfma_f32_32x32x16_bf16 v[66:81], v[228:231], v[240:243], v[66:81]
	ds_read_b128 v[212:215], v0 offset:4096
	s_waitcnt lgkmcnt(5)
	v_mfma_f32_32x32x16_bf16 v[50:65], v[224:227], v[244:247], v[50:65]
	ds_read_b128 v[216:219], v0 offset:8192
	v_mfma_f32_32x32x16_bf16 v[34:49], v[228:231], v[244:247], v[34:49]
	ds_read_b128 v[220:223], v0 offset:12288
	s_waitcnt lgkmcnt(6)
	v_mfma_f32_32x32x16_bf16 v[18:33], v[224:227], v[248:251], v[18:33]
	v_mfma_f32_32x32x16_bf16 v[2:17], v[228:231], v[248:251], v[2:17]
	v_add_u32_e32 v0, s14, v172
	v_add_u32_e32 v176, v0, v171
	v_add_u32_e32 v0, v0, v170
	s_waitcnt lgkmcnt(3)
	v_mfma_f32_32x32x16_bf16 v[114:129], v[200:203], v[208:211], v[114:129]
	ds_read_b128 v[224:227], v176 offset:32768
	v_mfma_f32_32x32x16_bf16 v[98:113], v[204:207], v[208:211], v[98:113]
	ds_read_b128 v[228:231], v176 offset:36864
	s_waitcnt lgkmcnt(4)
	v_mfma_f32_32x32x16_bf16 v[82:97], v[200:203], v[212:215], v[82:97]
	ds_read_b128 v[232:235], v0
	v_mfma_f32_32x32x16_bf16 v[66:81], v[204:207], v[212:215], v[66:81]
	ds_read_b128 v[240:243], v0 offset:4096
	s_waitcnt lgkmcnt(5)
	v_mfma_f32_32x32x16_bf16 v[50:65], v[200:203], v[216:219], v[50:65]
	ds_read_b128 v[244:247], v0 offset:8192
	v_mfma_f32_32x32x16_bf16 v[34:49], v[204:207], v[216:219], v[34:49]
	ds_read_b128 v[248:251], v0 offset:12288
	s_waitcnt lgkmcnt(6)
	v_mfma_f32_32x32x16_bf16 v[18:33], v[200:203], v[220:223], v[18:33]
	v_mfma_f32_32x32x16_bf16 v[2:17], v[204:207], v[220:223], v[2:17]
	s_waitcnt vmcnt(0)
	s_waitcnt vmcnt(0) lgkmcnt(0)
	s_barrier
;     ...
;     auto issue_at = [&](int mm0, int nn0, int kt, int buf) {
;       char* lb = L0 + buf * BUFB;
; #pragma unroll
;       for (int i = 0; i < 4; ++i) {
;         const int seg = wv * 4 + i, row = seg * 8 + gl_row;
;         const int c = (lane & 7) ^ ((row >> 1) & 7);
;         const u16* ap = (kt < g.split) ? g.a0 + (size_t)(mm0 + row) * g.ld0 + kt * g.ks0 : g.a1 + (size_t)(mm0 + row) * g.ld1 + (kt - g.split) * 64;
;         __builtin_amdgcn_global_load_lds((const unsigned*)(ap + c * 8), (__attribute__((address_space(3))) unsigned*)(lb + seg * 1024 + lane * 16), 16, 0, 0);
;       }
; #pragma unroll
;       for (int i = 0; i < BN / 64; ++i) {
;         const int seg = wv * (BN / 64) + i, row = seg * 8 + gl_row;
;         const int c = (lane & 7) ^ ((row >> 1) & 7);
;         __builtin_amdgcn_global_load_lds((const unsigned*)(g.W + (size_t)(nn0 + row) * g.K + kt * 64 + c * 8),
;                                          (__attribute__((address_space(3))) unsigned*)(lb + 256 * 128 + seg * 1024 + lane * 16), 16, 0, 0);
;       }
;     };
; template <int MODE, int EPI, int BN>
; DI void gemm_phase(CP p, const GArgs& g, int NT, char* smem) {
;     ...
;   for (int e = j; e < total; e += nj) {
;     const int grp = e / (8 * NT);
;     const int rem = e - grp * 8 * NT;
;     const int e2 = e + nj;
;     const bool has_next = can_chain && e2 < total;
;     const int grp2 = e2 / (8 * NT), rem2 = e2 - grp2 * 8 * NT;
;     const int chain = can_chain ? ((first ? 0 : 1) | (has_next ? 2 : 0)) : 0;
;     gemm_tile<MODE, EPI, BN>(p, g, x + 8 * (grp * 8 + (rem & 7)), rem >> 3, smem, chain, x + 8 * (grp2 * 8 + (rem2 & 7)), rem2 >> 3);
	v_mfma_f32_32x32x16_bf16 v[114:129], v[224:227], v[232:235], v[114:129]
	v_mfma_f32_32x32x16_bf16 v[98:113], v[228:231], v[232:235], v[98:113]
	v_mfma_f32_32x32x16_bf16 v[82:97], v[224:227], v[240:243], v[82:97]
	v_mfma_f32_32x32x16_bf16 v[66:81], v[228:231], v[240:243], v[66:81]
	v_mfma_f32_32x32x16_bf16 v[50:65], v[224:227], v[244:247], v[50:65]
	v_mfma_f32_32x32x16_bf16 v[34:49], v[228:231], v[244:247], v[34:49]
	v_mfma_f32_32x32x16_bf16 v[18:33], v[224:227], v[248:251], v[18:33]
	v_mfma_f32_32x32x16_bf16 v[2:17], v[228:231], v[248:251], v[2:17]
	s_cbranch_scc0 .LBB0_798
	s_add_i32 s95, s95, s76
	s_cmpk_gt_u32 s95, 0x9f
	s_cselect_b64 s[92:93], -1, 0
	s_and_b64 vcc, exec, s[92:93]
	s_cbranch_vccnz .LBB0_801
	s_mul_hi_u32 s2, s95, 0xcccccccd
	s_lshr_b32 s3, s2, 6
	s_mulk_i32 s3, 0xffb0
	s_lshl_b32 s11, s95, 3
	s_add_i32 s3, s3, s95
	s_and_b32 s2, s2, 0xffffc0
	s_and_b32 s11, s11, 56
	s_or_b32 s2, s2, s11
	v_readlane_b32 s11, v252, 38
	s_lshl_b32 s3, s3, 5
	s_or_b32 s2, s2, s11
	s_and_b32 s3, s3, 0xffffff00
	s_lshl_b32 s2, s2, 8
	v_add_u32_e32 v148, s3, v161
	v_add_u32_e32 v138, s2, v157
	v_ashrrev_i32_e32 v149, 31, v148
	v_ashrrev_i32_e32 v139, 31, v138
	v_lshl_add_u64 v[176:177], s[68:69], 0, v[136:137]
	v_lshl_add_u64 v[136:137], s[70:71], 0, v[136:137]
	v_lshlrev_b64 v[148:149], 11, v[148:149]
	v_add3_u32 v0, 0, v168, v169
	v_add_u32_e32 v140, s2, v161
	v_add_u32_e32 v142, s2, v165
	v_add_u32_e32 v144, s2, v167
	v_lshlrev_b64 v[138:139], 11, v[138:139]
	v_lshl_add_u64 v[136:137], v[136:137], 0, v[148:149]
	v_lshl_add_u64 v[148:149], s[70:71], 0, v[134:135]
	v_lshl_add_u64 v[134:135], s[68:69], 0, v[134:135]
	v_readfirstlane_b32 s2, v0
	v_lshl_add_u64 v[134:135], v[134:135], 0, v[138:139]
	s_mov_b32 m0, s2
	v_ashrrev_i32_e32 v141, 31, v140
	global_load_lds_dwordx4 v[134:135], off
	v_add3_u32 v134, 0, v160, v169
	v_ashrrev_i32_e32 v143, 31, v142
	v_lshlrev_b64 v[140:141], 11, v[140:141]
	v_readfirstlane_b32 s2, v134
	v_add3_u32 v135, 0, v162, v169
	v_lshlrev_b64 v[142:143], 11, v[142:143]
	v_lshl_add_u64 v[202:203], s[70:71], 0, v[132:133]
	v_lshl_add_u64 v[132:133], s[68:69], 0, v[132:133]
	v_lshl_add_u64 v[140:141], v[176:177], 0, v[140:141]
	s_mov_b32 m0, s2
	v_readfirstlane_b32 s2, v135
	v_lshl_add_u64 v[132:133], v[132:133], 0, v[142:143]
	global_load_lds_dwordx4 v[140:141], off
	s_mov_b32 m0, s2
	v_ashrrev_i32_e32 v145, 31, v144
	v_add_u32_e32 v146, s3, v157
	global_load_lds_dwordx4 v[132:133], off
	v_add3_u32 v132, 0, v166, v169
	v_ashrrev_i32_e32 v147, 31, v146
	v_lshl_add_u64 v[200:201], s[68:69], 0, v[130:131]
	v_lshlrev_b64 v[144:145], 11, v[144:145]
	v_readfirstlane_b32 s2, v132
	v_add_u32_e32 v0, 0x8000, v0
	v_add_u32_e32 v150, s3, v165
	v_add_u32_e32 v152, s3, v167
	v_lshlrev_b64 v[146:147], 11, v[146:147]
	v_lshl_add_u64 v[144:145], v[200:201], 0, v[144:145]
	s_mov_b32 m0, s2
	v_readfirstlane_b32 s2, v0
	v_add_u32_e32 v0, 0x8000, v134
	v_ashrrev_i32_e32 v151, 31, v150
	v_ashrrev_i32_e32 v153, 31, v152
	v_lshl_add_u64 v[146:147], v[148:149], 0, v[146:147]
	global_load_lds_dwordx4 v[144:145], off
	s_mov_b32 m0, s2
	v_readfirstlane_b32 s2, v0
	v_add_u32_e32 v0, 0x8000, v135
	v_lshlrev_b64 v[150:151], 11, v[150:151]
	v_lshlrev_b64 v[152:153], 11, v[152:153]
	global_load_lds_dwordx4 v[146:147], off
	s_mov_b32 m0, s2
	v_readfirstlane_b32 s2, v0
	v_add_u32_e32 v0, 0x8000, v132
	v_lshl_add_u64 v[152:153], s[70:71], 0, v[152:153]
	v_lshl_add_u64 v[150:151], v[202:203], 0, v[150:151]
	global_load_lds_dwordx4 v[136:137], off
	s_mov_b32 m0, s2
	v_readfirstlane_b32 s2, v0
	global_load_lds_dwordx4 v[150:151], off
	v_lshl_add_u64 v[130:131], v[152:153], 0, v[130:131]
	s_mov_b32 m0, s2
	s_nop 0
	global_load_lds_dwordx4 v[130:131], off

; #define MFMA(a, b, c) __builtin_amdgcn_mfma_f32_32x32x16_bf16((a), (b), (c), 0, 0, 0)
;     ...
;     auto issue_at = [&](int mm0, int nn0, int kt, int buf) {
;       char* lb = L0 + buf * BUFB;
; #pragma unroll
;       for (int i = 0; i < 4; ++i) {
;         const int seg = wv * 4 + i, row = seg * 8 + gl_row;
;         const int c = (lane & 7) ^ ((row >> 1) & 7);
;         const u16* ap = (kt < g.split) ? g.a0 + (size_t)(mm0 + row) * g.ld0 + kt * g.ks0 : g.a1 + (size_t)(mm0 + row) * g.ld1 + (kt - g.split) * 64;
;         __builtin_amdgcn_global_load_lds((const unsigned*)(ap + c * 8), (__attribute__((address_space(3))) unsigned*)(lb + seg * 1024 + lane * 16), 16, 0, 0);
;       }
; #pragma unroll
;       for (int i = 0; i < BN / 64; ++i) {
;         const int seg = wv * (BN / 64) + i, row = seg * 8 + gl_row;
;         const int c = (lane & 7) ^ ((row >> 1) & 7);
;         __builtin_amdgcn_global_load_lds((const unsigned*)(g.W + (size_t)(nn0 + row) * g.K + kt * 64 + c * 8),
;                                          (__attribute__((address_space(3))) unsigned*)(lb + 256 * 128 + seg * 1024 + lane * 16), 16, 0, 0);
;       }
;     };
;     ...
;     auto compute2 = [&](int buf) {
;       const char* lb = L0 + buf * BUFB;
; #pragma unroll
;       for (int ks = 0; ks < 4; ++ks) {
;         const int c = ks * 2 + hh;
;         bf16x8 wf[2], xf[MI];
; #pragma unroll
;         for (int j = 0; j < 2; ++j) { const int r = wn * 64 + j * 32 + l32; wf[j] = *(const bf16x8*)(lb + 256 * 128 + r * 128 + ((c ^ ((r >> 1) & 7)) << 4)); }
; #pragma unroll
;         for (int i = 0; i < MI; ++i) { const int r = wm * (MI * 32) + i * 32 + l32; xf[i] = *(const bf16x8*)(lb + r * 128 + ((c ^ ((r >> 1) & 7)) << 4)); }
; #pragma unroll
;         for (int i = 0; i < MI; ++i) {
;           acc[i][0] = MFMA(wf[0], xf[i], acc[i][0]);
;           acc[i][1] = MFMA(wf[1], xf[i], acc[i][1]);
;         }
;       }
;     };
.LBB0_1371:
	s_and_b32 s17, s16, 0x10000
	s_xor_b32 s43, s17, 0x10000
	s_add_i32 s43, s43, 0
	s_add_i32 s17, s17, 0
	v_add_u32_e32 v0, s17, v174
	v_add_u32_e32 v175, v0, v170
	v_add_u32_e32 v0, v0, v169
	ds_read_b128 v[200:203], v175 offset:32768
	ds_read_b128 v[204:207], v175 offset:36864
	ds_read_b128 v[208:211], v0
	ds_read_b128 v[212:215], v0 offset:4096
	ds_read_b128 v[216:219], v0 offset:8192
	ds_read_b128 v[220:223], v0 offset:12288
	v_add3_u32 v0, s43, v167, v168
	v_add3_u32 v175, s43, v157, v168
	v_readfirstlane_b32 s45, v0
	v_lshl_add_u64 v[176:177], v[152:153], 0, s[10:11]
	s_mov_b32 m0, s45
	v_readfirstlane_b32 s45, v175
	v_add3_u32 v178, s43, v159, v168
	global_load_lds_dwordx4 v[176:177], off
	v_lshl_add_u64 v[176:177], v[150:151], 0, s[10:11]
	s_mov_b32 m0, s45
	v_readfirstlane_b32 s45, v178
	v_add3_u32 v199, s43, v165, v168
	global_load_lds_dwordx4 v[176:177], off
	v_lshl_add_u64 v[176:177], v[148:149], 0, s[10:11]
	s_mov_b32 m0, s45
	v_readfirstlane_b32 s43, v199
	v_add_u32_e32 v0, 0x8000, v0
	global_load_lds_dwordx4 v[176:177], off
	v_lshl_add_u64 v[176:177], v[146:147], 0, s[10:11]
	s_mov_b32 m0, s43
	v_readfirstlane_b32 s43, v0
	v_add_u32_e32 v0, 0x8000, v175
	global_load_lds_dwordx4 v[176:177], off
	v_lshl_add_u64 v[176:177], v[144:145], 0, s[10:11]
	s_mov_b32 m0, s43
	v_readfirstlane_b32 s43, v0
	v_add_u32_e32 v0, 0x8000, v178
	global_load_lds_dwordx4 v[176:177], off
	v_lshl_add_u64 v[176:177], v[142:143], 0, s[10:11]
	s_mov_b32 m0, s43
	v_readfirstlane_b32 s43, v0
	v_add_u32_e32 v0, 0x8000, v199
	global_load_lds_dwordx4 v[176:177], off
	v_lshl_add_u64 v[176:177], v[140:141], 0, s[10:11]
	s_mov_b32 m0, s43
	v_readfirstlane_b32 s43, v0
	global_load_lds_dwordx4 v[176:177], off
	v_lshl_add_u64 v[176:177], v[138:139], 0, s[10:11]
	s_mov_b32 m0, s43
	global_load_lds_dwordx4 v[176:177], off
	v_add_u32_e32 v0, s17, v173
	v_add_u32_e32 v175, v0, v170
	v_add_u32_e32 v0, v0, v169
	s_waitcnt lgkmcnt(3)
	v_mfma_f32_32x32x16_bf16 v[114:129], v[200:203], v[208:211], v[114:129]
	s_add_i32 s16, s16, 0x10000
	s_add_u32 s10, s10, 0x80
	s_addc_u32 s11, s11, 0
	s_cmpk_eq_i32 s10, 0x780
	ds_read_b128 v[224:227], v175 offset:32768
	v_mfma_f32_32x32x16_bf16 v[98:113], v[204:207], v[208:211], v[98:113]
	ds_read_b128 v[228:231], v175 offset:36864
	s_waitcnt lgkmcnt(4)
	v_mfma_f32_32x32x16_bf16 v[82:97], v[200:203], v[212:215], v[82:97]
	ds_read_b128 v[232:235], v0
	v_mfma_f32_32x32x16_bf16 v[66:81], v[204:207], v[212:215], v[66:81]
	ds_read_b128 v[240:243], v0 offset:4096
	s_waitcnt lgkmcnt(5)
	v_mfma_f32_32x32x16_bf16 v[50:65], v[200:203], v[216:219], v[50:65]
	ds_read_b128 v[244:247], v0 offset:8192
	v_mfma_f32_32x32x16_bf16 v[34:49], v[204:207], v[216:219], v[34:49]
	ds_read_b128 v[248:251], v0 offset:12288
	s_waitcnt lgkmcnt(6)
	v_mfma_f32_32x32x16_bf16 v[18:33], v[200:203], v[220:223], v[18:33]
	v_mfma_f32_32x32x16_bf16 v[2:17], v[204:207], v[220:223], v[2:17]
	v_add_u32_e32 v0, s17, v172
	v_add_u32_e32 v175, v0, v170
	v_add_u32_e32 v0, v0, v169
	s_waitcnt lgkmcnt(3)
	v_mfma_f32_32x32x16_bf16 v[114:129], v[224:227], v[232:235], v[114:129]
	ds_read_b128 v[200:203], v175 offset:32768
	v_mfma_f32_32x32x16_bf16 v[98:113], v[228:231], v[232:235], v[98:113]
	ds_read_b128 v[204:207], v175 offset:36864
	s_waitcnt lgkmcnt(4)
	v_mfma_f32_32x32x16_bf16 v[82:97], v[224:227], v[240:243], v[82:97]
	ds_read_b128 v[208:211], v0
	v_mfma_f32_32x32x16_bf16 v[66:81], v[228:231], v[240:243], v[66:81]
	ds_read_b128 v[212:215], v0 offset:4096
	s_waitcnt lgkmcnt(5)
	v_mfma_f32_32x32x16_bf16 v[50:65], v[224:227], v[244:247], v[50:65]
	ds_read_b128 v[216:219], v0 offset:8192
	v_mfma_f32_32x32x16_bf16 v[34:49], v[228:231], v[244:247], v[34:49]
	ds_read_b128 v[220:223], v0 offset:12288
	s_waitcnt lgkmcnt(6)
	v_mfma_f32_32x32x16_bf16 v[18:33], v[224:227], v[248:251], v[18:33]
	v_mfma_f32_32x32x16_bf16 v[2:17], v[228:231], v[248:251], v[2:17]
	v_add_u32_e32 v0, s17, v171
	v_add_u32_e32 v175, v0, v170
	v_add_u32_e32 v0, v0, v169
	s_waitcnt lgkmcnt(3)
	v_mfma_f32_32x32x16_bf16 v[114:129], v[200:203], v[208:211], v[114:129]
	ds_read_b128 v[224:227], v175 offset:32768
	v_mfma_f32_32x32x16_bf16 v[98:113], v[204:207], v[208:211], v[98:113]
	ds_read_b128 v[228:231], v175 offset:36864
	s_waitcnt lgkmcnt(4)
	v_mfma_f32_32x32x16_bf16 v[82:97], v[200:203], v[212:215], v[82:97]
	ds_read_b128 v[232:235], v0
	v_mfma_f32_32x32x16_bf16 v[66:81], v[204:207], v[212:215], v[66:81]
	ds_read_b128 v[240:243], v0 offset:4096
	s_waitcnt lgkmcnt(5)
	v_mfma_f32_32x32x16_bf16 v[50:65], v[200:203], v[216:219], v[50:65]
	ds_read_b128 v[244:247], v0 offset:8192
	v_mfma_f32_32x32x16_bf16 v[34:49], v[204:207], v[216:219], v[34:49]
	ds_read_b128 v[248:251], v0 offset:12288
	s_waitcnt lgkmcnt(6)
	v_mfma_f32_32x32x16_bf16 v[18:33], v[200:203], v[220:223], v[18:33]
	v_mfma_f32_32x32x16_bf16 v[2:17], v[204:207], v[220:223], v[2:17]
	s_waitcnt vmcnt(0)
	s_waitcnt vmcnt(0) lgkmcnt(0)
	s_barrier
;     ...
;     auto issue_at = [&](int mm0, int nn0, int kt, int buf) {
;       char* lb = L0 + buf * BUFB;
; #pragma unroll
;       for (int i = 0; i < 4; ++i) {
;         const int seg = wv * 4 + i, row = seg * 8 + gl_row;
;         const int c = (lane & 7) ^ ((row >> 1) & 7);
;         const u16* ap = (kt < g.split) ? g.a0 + (size_t)(mm0 + row) * g.ld0 + kt * g.ks0 : g.a1 + (size_t)(mm0 + row) * g.ld1 + (kt - g.split) * 64;
;         __builtin_amdgcn_global_load_lds((const unsigned*)(ap + c * 8), (__attribute__((address_space(3))) unsigned*)(lb + seg * 1024 + lane * 16), 16, 0, 0);
;       }
; #pragma unroll
;       for (int i = 0; i < BN / 64; ++i) {
;         const int seg = wv * (BN / 64) + i, row = seg * 8 + gl_row;
;         const int c = (lane & 7) ^ ((row >> 1) & 7);
;         __builtin_amdgcn_global_load_lds((const unsigned*)(g.W + (size_t)(nn0 + row) * g.K + kt * 64 + c * 8),
;                                          (__attribute__((address_space(3))) unsigned*)(lb + 256 * 128 + seg * 1024 + lane * 16), 16, 0, 0);
;       }
;     };
; template <int MODE, int EPI, int BN>
; DI void gemm_phase(CP p, const GArgs& g, int NT, char* smem) {
;     ...
;   for (int e = j; e < total; e += nj) {
;     const int grp = e / (8 * NT);
;     const int rem = e - grp * 8 * NT;
;     const int e2 = e + nj;
;     const bool has_next = can_chain && e2 < total;
;     const int grp2 = e2 / (8 * NT), rem2 = e2 - grp2 * 8 * NT;
;     const int chain = can_chain ? ((first ? 0 : 1) | (has_next ? 2 : 0)) : 0;
;     gemm_tile<MODE, EPI, BN>(p, g, x + 8 * (grp * 8 + (rem & 7)), rem >> 3, smem, chain, x + 8 * (grp2 * 8 + (rem2 & 7)), rem2 >> 3);
	v_mfma_f32_32x32x16_bf16 v[114:129], v[224:227], v[232:235], v[114:129]
	v_mfma_f32_32x32x16_bf16 v[98:113], v[228:231], v[232:235], v[98:113]
	v_mfma_f32_32x32x16_bf16 v[82:97], v[224:227], v[240:243], v[82:97]
	v_mfma_f32_32x32x16_bf16 v[66:81], v[228:231], v[240:243], v[66:81]
	v_mfma_f32_32x32x16_bf16 v[50:65], v[224:227], v[244:247], v[50:65]
	v_mfma_f32_32x32x16_bf16 v[34:49], v[228:231], v[244:247], v[34:49]
	v_mfma_f32_32x32x16_bf16 v[18:33], v[224:227], v[248:251], v[18:33]
	v_mfma_f32_32x32x16_bf16 v[2:17], v[228:231], v[248:251], v[2:17]
	s_cbranch_scc0 .LBB0_1371
	s_add_i32 s51, s51, s50
	s_cmpk_gt_u32 s51, 0x15f
	s_cselect_b64 s[10:11], -1, 0
	s_and_b64 vcc, exec, s[10:11]
	s_cbranch_vccnz .LBB0_1374
	s_mul_hi_u32 s16, s51, 0xba2e8ba3
	s_lshr_b32 s16, s16, 7
	s_mul_i32 s17, s16, 0xffffff50
	s_lshl_b32 s43, s51, 3
	s_add_i32 s17, s17, s51
	s_lshl_b32 s16, s16, 6
	s_and_b32 s43, s43, 56
	s_or_b32 s16, s16, s43
	s_lshl_b32 s17, s17, 5
	s_or_b32 s16, s16, s72
	s_and_b32 s17, s17, 0xffffff00
	s_lshl_b32 s16, s16, 8
	v_add_u32_e32 v148, s17, v158
	v_add_u32_e32 v138, s16, v156
	v_ashrrev_i32_e32 v149, 31, v148
	v_ashrrev_i32_e32 v139, 31, v138
	v_lshl_add_u64 v[176:177], s[46:47], 0, v[136:137]
	v_lshl_add_u64 v[136:137], s[48:49], 0, v[136:137]
	v_lshlrev_b64 v[148:149], 11, v[148:149]
	v_add3_u32 v0, 0, v167, v168
	v_add_u32_e32 v140, s16, v158
	v_add_u32_e32 v142, s16, v164
	v_add_u32_e32 v144, s16, v166
	v_lshlrev_b64 v[138:139], 11, v[138:139]
	v_lshl_add_u64 v[136:137], v[136:137], 0, v[148:149]
	v_lshl_add_u64 v[148:149], s[48:49], 0, v[134:135]
	v_lshl_add_u64 v[134:135], s[46:47], 0, v[134:135]
	v_readfirstlane_b32 s16, v0
	v_lshl_add_u64 v[134:135], v[134:135], 0, v[138:139]
	s_mov_b32 m0, s16
	v_ashrrev_i32_e32 v141, 31, v140
	global_load_lds_dwordx4 v[134:135], off
	v_add3_u32 v134, 0, v157, v168
	v_ashrrev_i32_e32 v143, 31, v142
	v_lshlrev_b64 v[140:141], 11, v[140:141]
	v_readfirstlane_b32 s16, v134
	v_add3_u32 v135, 0, v159, v168
	v_lshlrev_b64 v[142:143], 11, v[142:143]
	v_lshl_add_u64 v[202:203], s[48:49], 0, v[132:133]
	v_lshl_add_u64 v[132:133], s[46:47], 0, v[132:133]
	v_lshl_add_u64 v[140:141], v[176:177], 0, v[140:141]
	s_mov_b32 m0, s16
	v_readfirstlane_b32 s16, v135
	v_lshl_add_u64 v[132:133], v[132:133], 0, v[142:143]
	global_load_lds_dwordx4 v[140:141], off
	s_mov_b32 m0, s16
	v_ashrrev_i32_e32 v145, 31, v144
	v_add_u32_e32 v146, s17, v156
	global_load_lds_dwordx4 v[132:133], off
	v_add3_u32 v132, 0, v165, v168
	v_ashrrev_i32_e32 v147, 31, v146
	v_lshl_add_u64 v[200:201], s[46:47], 0, v[130:131]
	v_lshlrev_b64 v[144:145], 11, v[144:145]
	v_readfirstlane_b32 s16, v132
	v_add_u32_e32 v0, 0x8000, v0
	v_add_u32_e32 v150, s17, v164
	v_add_u32_e32 v152, s17, v166
	v_lshlrev_b64 v[146:147], 11, v[146:147]
	v_lshl_add_u64 v[144:145], v[200:201], 0, v[144:145]
	s_mov_b32 m0, s16
	v_readfirstlane_b32 s16, v0
	v_add_u32_e32 v0, 0x8000, v134
	v_ashrrev_i32_e32 v151, 31, v150
	v_ashrrev_i32_e32 v153, 31, v152
	v_lshl_add_u64 v[146:147], v[148:149], 0, v[146:147]
	global_load_lds_dwordx4 v[144:145], off
	s_mov_b32 m0, s16
	v_readfirstlane_b32 s16, v0
	v_add_u32_e32 v0, 0x8000, v135
	v_lshlrev_b64 v[150:151], 11, v[150:151]
	v_lshlrev_b64 v[152:153], 11, v[152:153]
	global_load_lds_dwordx4 v[146:147], off
	s_mov_b32 m0, s16
	v_readfirstlane_b32 s16, v0
	v_add_u32_e32 v0, 0x8000, v132
	v_lshl_add_u64 v[152:153], s[48:49], 0, v[152:153]
	v_lshl_add_u64 v[150:151], v[202:203], 0, v[150:151]
	global_load_lds_dwordx4 v[136:137], off
	s_mov_b32 m0, s16
	v_readfirstlane_b32 s16, v0
	global_load_lds_dwordx4 v[150:151], off
	v_lshl_add_u64 v[130:131], v[152:153], 0, v[130:131]
	s_mov_b32 m0, s16
	s_nop 0
	global_load_lds_dwordx4 v[130:131], off

; #define LAS __attribute__((address_space(3)))
; template <bool COOP>
; __global__ void __launch_bounds__(NTHR) mega(Params pp, int lo, int hi) {
;   extern __shared__ __attribute__((aligned(16))) char smem[];
;   const __attribute__((address_space(4))) Params* kp = (const __attribute__((address_space(4))) Params*)__builtin_amdgcn_kernarg_segment_ptr();
;   volatile LAS unsigned* st = (volatile LAS unsigned*)(smem + SMEM_BYTES - 32);
	.amdhsa_kernel _Z4megaILb1EEv6Paramsii
		.amdhsa_group_segment_fixed_size 8192
		.amdhsa_private_segment_fixed_size 0
		.amdhsa_kernarg_size 616
		.amdhsa_user_sgpr_count 2
		.amdhsa_user_sgpr_dispatch_ptr 0
		.amdhsa_user_sgpr_queue_ptr 0
		.amdhsa_user_sgpr_kernarg_segment_ptr 1
		.amdhsa_user_sgpr_dispatch_id 0
		.amdhsa_user_sgpr_kernarg_preload_length 0
		.amdhsa_user_sgpr_kernarg_preload_offset 0
		.amdhsa_user_sgpr_private_segment_size 0
		.amdhsa_uses_dynamic_stack 0
		.amdhsa_enable_private_segment 0
		.amdhsa_system_sgpr_workgroup_id_x 1
		.amdhsa_system_sgpr_workgroup_id_y 0
		.amdhsa_system_sgpr_workgroup_id_z 0
		.amdhsa_system_sgpr_workgroup_info 0
		.amdhsa_system_vgpr_workitem_id 2
		.amdhsa_next_free_vgpr 255
		.amdhsa_next_free_sgpr 100
		.amdhsa_accum_offset 256
		.amdhsa_reserve_vcc 1
		.amdhsa_float_round_mode_32 0
		.amdhsa_float_round_mode_16_64 0
		.amdhsa_float_denorm_mode_32 3
		.amdhsa_float_denorm_mode_16_64 3
		.amdhsa_dx10_clamp 1
		.amdhsa_ieee_mode 1
		.amdhsa_fp16_overflow 0
		.amdhsa_tg_split 0
		.amdhsa_exception_fp_ieee_invalid_op 0
		.amdhsa_exception_fp_denorm_src 0
		.amdhsa_exception_fp_ieee_div_zero 0
		.amdhsa_exception_fp_ieee_overflow 0
		.amdhsa_exception_fp_ieee_underflow 0
		.amdhsa_exception_fp_ieee_inexact 0
		.amdhsa_exception_int_div_zero 0
	.end_amdhsa_kernel

; #define LAS __attribute__((address_space(3)))
; template <bool COOP>
; __global__ void __launch_bounds__(NTHR) mega(Params pp, int lo, int hi) {
;   extern __shared__ __attribute__((aligned(16))) char smem[];
;   const __attribute__((address_space(4))) Params* kp = (const __attribute__((address_space(4))) Params*)__builtin_amdgcn_kernarg_segment_ptr();
;   volatile LAS unsigned* st = (volatile LAS unsigned*)(smem + SMEM_BYTES - 32);
amdhsa.kernels:
  - .agpr_count:     0
    .args:
      - .offset:         0
        .size:           352
        .value_kind:     by_value
      - .offset:         352
        .size:           4
        .value_kind:     by_value
      - .offset:         356
        .size:           4
        .value_kind:     by_value
      - .offset:         360
        .size:           4
        .value_kind:     hidden_block_count_x
      - .offset:         364
        .size:           4
        .value_kind:     hidden_block_count_y
      - .offset:         368
        .size:           4
        .value_kind:     hidden_block_count_z
      - .offset:         372
        .size:           2
        .value_kind:     hidden_group_size_x
      - .offset:         374
        .size:           2
        .value_kind:     hidden_group_size_y
      - .offset:         376
        .size:           2
        .value_kind:     hidden_group_size_z
      - .offset:         378
        .size:           2
        .value_kind:     hidden_remainder_x
      - .offset:         380
        .size:           2
        .value_kind:     hidden_remainder_y
      - .offset:         382
        .size:           2
        .value_kind:     hidden_remainder_z
      - .offset:         400
        .size:           8
        .value_kind:     hidden_global_offset_x
      - .offset:         408
        .size:           8
        .value_kind:     hidden_global_offset_y
      - .offset:         416
        .size:           8
        .value_kind:     hidden_global_offset_z
      - .offset:         424
        .size:           2
        .value_kind:     hidden_grid_dims
      - .offset:         448
        .size:           8
        .value_kind:     hidden_multigrid_sync_arg
      - .offset:         480
        .size:           4
        .value_kind:     hidden_dynamic_lds_size
    .group_segment_fixed_size: 8192
    .kernarg_segment_align: 8
    .kernarg_segment_size: 616
    .language:       OpenCL C
    .language_version:
      - 2
      - 0
    .max_flat_workgroup_size: 512
    .name:           _Z4megaILb1EEv6Paramsii
    .private_segment_fixed_size: 0
    .sgpr_count:     106
    .sgpr_spill_count: 137
    .symbol:         _Z4megaILb1EEv6Paramsii.kd
    .uniform_work_group_size: 1
    .uses_dynamic_stack: false
    .vgpr_count:     255
    .vgpr_spill_count: 0
    .wavefront_size: 64
